# v31 + nt hint on the 16 residual-stream loads of the residual-GEMM epilogue
# baseline (speedup 1.0000x reference)
; DI unsigned pkh2(float lo, float hi) { return __builtin_bit_cast(unsigned, __builtin_amdgcn_cvt_pkrtz(lo, hi)); }
; DI float hlo(unsigned u) { return (float)__builtin_bit_cast(f16x2_t, u).x; }
; DI float hhi(unsigned u) { return (float)__builtin_bit_cast(f16x2_t, u).y; }
;     DI void operator()(const pg8::f32x4 (&acc)[2][2][4][2], const pg8::Unit& u, int wr, int wc, int fr, int fq) const {
;         const int mi = (u.pm < 128) ? (u.pm >> 4) : 8;
;         const float* gp = modg + (size_t)mi * 9216;
;         const int row0 = u.pm * 256 + wr * 64 + fr, col0 = u.pn * 256 + wc * 32 + 8 * fq;
;         const float scale = *scale_p;
; #pragma unroll
;         for (int bj = 0; bj < 2; ++bj) {
;             f32x4 gs[2], gq[2], bq[2];
; #pragma unroll
;             for (int n = 0; n < 2; ++n) { const f32x4 g = *(const f32x4*)(gp + col0 + bj * 128 + 4 * n); gs[n] = (g + 1.0f) * scale;
;                 gq[n] = *(const f32x4*)(gprev + col0 + bj * 128 + 4 * n) * ALPHA; bq[n] = *(const f32x4*)(bprev + col0 + bj * 128 + 4 * n) * ALPHA; }
; #pragma unroll
;             for (int ai = 0; ai < 2; ++ai) {
;                 u32x4 xv[4]; f32x2 st[4];
; #pragma unroll
;                 for (int m = 0; m < 4; ++m) { const int row = row0 + ai * 128 + m * 16; xv[m] = *(const u32x4*)(X + (size_t)row * DM + col0 + bj * 128); st[m] = stat[row]; }
;                 __builtin_amdgcn_sched_barrier(0);
; #pragma unroll
;                 for (int m = 0; m < 4; ++m) {
;                     const f32x4 x0 = {hlo(xv[m].x), hhi(xv[m].x), hlo(xv[m].y), hhi(xv[m].y)}, x1 = {hlo(xv[m].z), hhi(xv[m].z), hlo(xv[m].w), hhi(xv[m].w)};
;                     const f32x4 y0 = (x0 - st[m].x) * st[m].y * gq[0] + bq[0] + gs[0] * acc[ai][bj][m][0];
;                     const f32x4 y1 = (x1 - st[m].x) * st[m].y * gq[1] + bq[1] + gs[1] * acc[ai][bj][m][1];
;                     u32x4 w; w.x = pkh2(y0.x, y0.y); w.y = pkh2(y0.z, y0.w); w.z = pkh2(y1.x, y1.y); w.w = pkh2(y1.z, y1.w);
;                     *(u32x4*)(X + (size_t)(row0 + ai * 128 + m * 16) * DM + col0 + bj * 128) = w;
.LBB0_886:
	s_lshl_b64 s[30:31], s[30:31], 2
	v_lshl_or_b32 v138, s56, 8, v225
	s_add_u32 s30, s46, s30
	v_ashrrev_i32_e32 v139, 31, v138
	s_addc_u32 s31, s47, s31
	v_lshlrev_b64 v[142:143], 2, v[138:139]
	v_lshl_add_u64 v[158:159], s[30:31], 0, v[142:143]
	global_load_dword v140, v147, s[6:7]
	global_load_dwordx4 v[160:163], v[158:159], off offset:16
	global_load_dwordx4 v[164:167], v[158:159], off
	v_lshl_add_u64 v[154:155], s[20:21], 0, v[142:143]
	v_lshl_add_u64 v[142:143], s[22:23], 0, v[142:143]
	global_load_dwordx4 v[204:207], v[154:155], off offset:16
	global_load_dwordx4 v[168:171], v[154:155], off
	global_load_dwordx4 v[228:231], v[142:143], off offset:16
	global_load_dwordx4 v[176:179], v[142:143], off
	s_mov_b32 s34, 0x3fd744fd
	v_lshl_add_u32 v202, s55, 8, v223
	v_lshlrev_b64 v[196:197], 1, v[138:139]
	v_ashrrev_i32_e32 v203, 31, v202
	v_lshl_add_u64 v[198:199], s[24:25], 0, v[196:197]
	v_lshlrev_b64 v[200:201], 11, v[202:203]
	v_lshl_add_u64 v[138:139], v[202:203], 3, s[26:27]
	s_waitcnt vmcnt(4)
	v_pk_add_f32 v[160:161], v[160:161], 1.0 op_sel_hi:[1,0]
	v_pk_add_f32 v[164:165], v[164:165], 1.0 op_sel_hi:[1,0]
	v_pk_add_f32 v[156:157], v[166:167], 1.0 op_sel_hi:[1,0]
	v_pk_mul_f32 v[174:175], v[140:141], v[164:165] op_sel_hi:[0,1]
	v_pk_mul_f32 v[172:173], v[140:141], v[156:157] op_sel_hi:[0,1]
	v_pk_add_f32 v[156:157], v[162:163], 1.0 op_sel_hi:[1,0]
	v_or_b32_e32 v162, 16, v202
	v_ashrrev_i32_e32 v163, 31, v162
	v_lshlrev_b64 v[246:247], 11, v[162:163]
	v_lshl_add_u64 v[162:163], v[162:163], 3, s[26:27]
	s_waitcnt vmcnt(3)
	v_pk_mul_f32 v[184:185], v[206:207], s[34:35] op_sel_hi:[1,0]
	s_waitcnt vmcnt(2)
	v_pk_mul_f32 v[180:181], v[170:171], s[34:35] op_sel_hi:[1,0]
	v_pk_mul_f32 v[182:183], v[168:169], s[34:35] op_sel_hi:[1,0]
	v_or_b32_e32 v206, 32, v202
	v_ashrrev_i32_e32 v207, 31, v206
	v_lshlrev_b64 v[150:151], 11, v[206:207]
	v_pk_mul_f32 v[186:187], v[204:205], s[34:35] op_sel_hi:[1,0]
	v_lshl_add_u64 v[204:205], v[198:199], 0, v[150:151]
	v_lshl_add_u64 v[206:207], v[206:207], 3, s[26:27]
	v_mov_b32_e32 v164, v204
	v_mov_b32_e32 v165, v205
	v_mov_b32_e32 v166, v206
	v_mov_b32_e32 v167, v207
	global_load_dwordx4 v[236:239], v[164:165], off nt
	global_load_dwordx2 v[206:207], v[166:167], off
	global_load_dwordx2 v[244:245], v[138:139], off
	global_load_dwordx2 v[248:249], v[162:163], off
	s_waitcnt vmcnt(5)
	v_pk_mul_f32 v[188:189], v[230:231], s[34:35] op_sel_hi:[1,0]
	v_or_b32_e32 v170, 48, v202
	v_ashrrev_i32_e32 v171, 31, v170
	v_lshlrev_b64 v[202:203], 11, v[170:171]
	s_waitcnt vmcnt(4)
	v_pk_mul_f32 v[192:193], v[178:179], s[34:35] op_sel_hi:[1,0]
	v_pk_mul_f32 v[194:195], v[176:177], s[34:35] op_sel_hi:[1,0]
	v_pk_mul_f32 v[176:177], v[140:141], v[156:157] op_sel_hi:[0,1]
	v_pk_mul_f32 v[178:179], v[140:141], v[160:161] op_sel_hi:[0,1]
	v_pk_mul_f32 v[190:191], v[228:229], s[34:35] op_sel_hi:[1,0]
	v_lshl_add_u64 v[156:157], v[198:199], 0, v[200:201]
	v_lshl_add_u64 v[160:161], v[198:199], 0, v[246:247]
	v_lshl_add_u64 v[168:169], v[198:199], 0, v[202:203]
	v_lshl_add_u64 v[170:171], v[170:171], 3, s[26:27]
	global_load_dwordx4 v[228:231], v[156:157], off nt
	global_load_dwordx4 v[232:235], v[160:161], off nt
	global_load_dwordx4 v[240:243], v[168:169], off nt
	global_load_dwordx2 v[204:205], v[170:171], off
	s_waitcnt vmcnt(3)
	v_cvt_f32_f16_sdwa v227, v228 dst_sel:DWORD dst_unused:UNUSED_PAD src0_sel:WORD_1
	v_cvt_f32_f16_e32 v228, v228
	v_cvt_f32_f16_sdwa v250, v229 dst_sel:DWORD dst_unused:UNUSED_PAD src0_sel:WORD_1
	v_cvt_f32_f16_e32 v145, v229
	v_cvt_f32_f16_sdwa v218, v230 dst_sel:DWORD dst_unused:UNUSED_PAD src0_sel:WORD_1
	v_cvt_f32_f16_e32 v209, v230
	v_cvt_f32_f16_sdwa v219, v231 dst_sel:DWORD dst_unused:UNUSED_PAD src0_sel:WORD_1
	v_cvt_f32_f16_e32 v220, v231
	v_sub_f32_e32 v228, v228, v244
	v_sub_f32_e32 v229, v227, v244
	v_sub_f32_e32 v230, v145, v244
	v_sub_f32_e32 v231, v250, v244
	v_pk_mul_f32 v[228:229], v[244:245], v[228:229] op_sel:[1,0]
	v_pk_mul_f32 v[230:231], v[244:245], v[230:231] op_sel:[1,0]
	v_pk_fma_f32 v[228:229], v[182:183], v[228:229], v[194:195]
	v_pk_fma_f32 v[230:231], v[180:181], v[230:231], v[192:193]
	v_pk_fma_f32 v[124:125], v[124:125], v[174:175], v[228:229]
	v_sub_f32_e32 v228, v209, v244
	v_sub_f32_e32 v229, v218, v244
	v_pk_fma_f32 v[126:127], v[126:127], v[172:173], v[230:231]
	v_sub_f32_e32 v230, v220, v244
	v_sub_f32_e32 v231, v219, v244
	v_pk_mul_f32 v[228:229], v[244:245], v[228:229] op_sel:[1,0]
	v_pk_mul_f32 v[230:231], v[244:245], v[230:231] op_sel:[1,0]
	v_pk_fma_f32 v[228:229], v[186:187], v[228:229], v[190:191]
	v_pk_fma_f32 v[230:231], v[184:185], v[230:231], v[188:189]
	v_pk_fma_f32 v[120:121], v[120:121], v[178:179], v[228:229]
	v_pk_fma_f32 v[230:231], v[122:123], v[176:177], v[230:231]
	v_cvt_pkrtz_f16_f32 v122, v124, v125
	v_cvt_pkrtz_f16_f32 v124, v120, v121
	v_lshl_add_u64 v[120:121], s[24:25], 0, v[200:201]
	v_cvt_pkrtz_f16_f32 v123, v126, v127
	v_cvt_pkrtz_f16_f32 v125, v230, v231
	v_lshl_add_u64 v[120:121], v[120:121], 0, v[196:197]
	global_store_dwordx4 v[120:121], v[122:125], off
	s_waitcnt vmcnt(3)
; DI unsigned pkh2(float lo, float hi) { return __builtin_bit_cast(unsigned, __builtin_amdgcn_cvt_pkrtz(lo, hi)); }
; DI float hlo(unsigned u) { return (float)__builtin_bit_cast(f16x2_t, u).x; }
; DI float hhi(unsigned u) { return (float)__builtin_bit_cast(f16x2_t, u).y; }
;     DI void operator()(const pg8::f32x4 (&acc)[2][2][4][2], const pg8::Unit& u, int wr, int wc, int fr, int fq) const {
;     ...
;             for (int ai = 0; ai < 2; ++ai) {
;                 u32x4 xv[4]; f32x2 st[4];
; #pragma unroll
;                 for (int m = 0; m < 4; ++m) { const int row = row0 + ai * 128 + m * 16; xv[m] = *(const u32x4*)(X + (size_t)row * DM + col0 + bj * 128); st[m] = stat[row]; }
;                 __builtin_amdgcn_sched_barrier(0);
; #pragma unroll
;                 for (int m = 0; m < 4; ++m) {
;                     const f32x4 x0 = {hlo(xv[m].x), hhi(xv[m].x), hlo(xv[m].y), hhi(xv[m].y)}, x1 = {hlo(xv[m].z), hhi(xv[m].z), hlo(xv[m].w), hhi(xv[m].w)};
;                     const f32x4 y0 = (x0 - st[m].x) * st[m].y * gq[0] + bq[0] + gs[0] * acc[ai][bj][m][0];
;                     const f32x4 y1 = (x1 - st[m].x) * st[m].y * gq[1] + bq[1] + gs[1] * acc[ai][bj][m][1];
;                     u32x4 w; w.x = pkh2(y0.x, y0.y); w.y = pkh2(y0.z, y0.w); w.z = pkh2(y1.x, y1.y); w.w = pkh2(y1.z, y1.w);
;                     *(u32x4*)(X + (size_t)(row0 + ai * 128 + m * 16) * DM + col0 + bj * 128) = w;
	v_cvt_f32_f16_sdwa v126, v234 dst_sel:DWORD dst_unused:UNUSED_PAD src0_sel:WORD_1
	v_cvt_f32_f16_e32 v127, v234
	v_cvt_f32_f16_sdwa v123, v232 dst_sel:DWORD dst_unused:UNUSED_PAD src0_sel:WORD_1
	v_cvt_f32_f16_e32 v122, v232
	v_cvt_f32_f16_sdwa v125, v233 dst_sel:DWORD dst_unused:UNUSED_PAD src0_sel:WORD_1
	v_cvt_f32_f16_e32 v124, v233
	v_cvt_f32_f16_sdwa v145, v235 dst_sel:DWORD dst_unused:UNUSED_PAD src0_sel:WORD_1
	v_cvt_f32_f16_e32 v209, v235
	v_sub_f32_e32 v122, v122, v248
	v_sub_f32_e32 v123, v123, v248
	v_sub_f32_e32 v124, v124, v248
	v_sub_f32_e32 v125, v125, v248
	v_pk_mul_f32 v[122:123], v[248:249], v[122:123] op_sel:[1,0]
	v_pk_mul_f32 v[124:125], v[248:249], v[124:125] op_sel:[1,0]
	v_pk_fma_f32 v[122:123], v[182:183], v[122:123], v[194:195]
	v_pk_fma_f32 v[124:125], v[180:181], v[124:125], v[192:193]
	v_pk_fma_f32 v[116:117], v[116:117], v[174:175], v[122:123]
	v_sub_f32_e32 v122, v127, v248
	v_sub_f32_e32 v123, v126, v248
	v_pk_fma_f32 v[118:119], v[118:119], v[172:173], v[124:125]
	v_sub_f32_e32 v124, v209, v248
	v_sub_f32_e32 v125, v145, v248
	v_pk_mul_f32 v[122:123], v[248:249], v[122:123] op_sel:[1,0]
	v_pk_mul_f32 v[124:125], v[248:249], v[124:125] op_sel:[1,0]
	v_pk_fma_f32 v[122:123], v[186:187], v[122:123], v[190:191]
	v_pk_fma_f32 v[124:125], v[184:185], v[124:125], v[188:189]
	v_pk_fma_f32 v[112:113], v[112:113], v[178:179], v[122:123]
	v_pk_fma_f32 v[124:125], v[114:115], v[176:177], v[124:125]
	v_cvt_pkrtz_f16_f32 v114, v116, v117
	v_cvt_pkrtz_f16_f32 v116, v112, v113
	v_lshl_add_u64 v[112:113], s[24:25], 0, v[246:247]
	v_cvt_pkrtz_f16_f32 v115, v118, v119
	v_cvt_pkrtz_f16_f32 v117, v124, v125
	v_lshl_add_u64 v[112:113], v[112:113], 0, v[196:197]
	global_store_dwordx4 v[112:113], v[114:117], off
	v_cvt_f32_f16_sdwa v118, v238 dst_sel:DWORD dst_unused:UNUSED_PAD src0_sel:WORD_1
	v_cvt_f32_f16_e32 v119, v238
	v_cvt_f32_f16_sdwa v115, v236 dst_sel:DWORD dst_unused:UNUSED_PAD src0_sel:WORD_1
	v_cvt_f32_f16_e32 v114, v236
	v_cvt_f32_f16_sdwa v117, v237 dst_sel:DWORD dst_unused:UNUSED_PAD src0_sel:WORD_1
	v_cvt_f32_f16_e32 v116, v237
	v_cvt_f32_f16_sdwa v122, v239 dst_sel:DWORD dst_unused:UNUSED_PAD src0_sel:WORD_1
	v_cvt_f32_f16_e32 v123, v239
	v_sub_f32_e32 v114, v114, v206
	v_sub_f32_e32 v115, v115, v206
	v_sub_f32_e32 v116, v116, v206
	v_sub_f32_e32 v117, v117, v206
	v_pk_mul_f32 v[114:115], v[206:207], v[114:115] op_sel:[1,0]
	v_pk_mul_f32 v[116:117], v[206:207], v[116:117] op_sel:[1,0]
	v_pk_fma_f32 v[114:115], v[182:183], v[114:115], v[194:195]
	v_pk_fma_f32 v[116:117], v[180:181], v[116:117], v[192:193]
	v_pk_fma_f32 v[108:109], v[108:109], v[174:175], v[114:115]
	v_sub_f32_e32 v114, v119, v206
	v_sub_f32_e32 v115, v118, v206
	v_pk_fma_f32 v[110:111], v[110:111], v[172:173], v[116:117]
	v_sub_f32_e32 v116, v123, v206
	v_sub_f32_e32 v117, v122, v206
	v_pk_mul_f32 v[114:115], v[206:207], v[114:115] op_sel:[1,0]
	v_pk_mul_f32 v[116:117], v[206:207], v[116:117] op_sel:[1,0]
	v_pk_fma_f32 v[114:115], v[186:187], v[114:115], v[190:191]
	v_pk_fma_f32 v[116:117], v[184:185], v[116:117], v[188:189]
	v_pk_fma_f32 v[104:105], v[104:105], v[178:179], v[114:115]
	v_pk_fma_f32 v[116:117], v[106:107], v[176:177], v[116:117]
	v_cvt_pkrtz_f16_f32 v106, v108, v109
	v_cvt_pkrtz_f16_f32 v108, v104, v105
	v_lshl_add_u64 v[104:105], s[24:25], 0, v[150:151]
	v_cvt_pkrtz_f16_f32 v107, v110, v111
	v_cvt_pkrtz_f16_f32 v109, v116, v117
	v_lshl_add_u64 v[104:105], v[104:105], 0, v[196:197]
	global_store_dwordx4 v[104:105], v[106:109], off
	s_waitcnt vmcnt(4)
	v_cvt_f32_f16_sdwa v110, v242 dst_sel:DWORD dst_unused:UNUSED_PAD src0_sel:WORD_1
	v_cvt_f32_f16_e32 v111, v242
	v_cvt_f32_f16_sdwa v107, v240 dst_sel:DWORD dst_unused:UNUSED_PAD src0_sel:WORD_1
	v_cvt_f32_f16_e32 v106, v240
	v_cvt_f32_f16_sdwa v109, v241 dst_sel:DWORD dst_unused:UNUSED_PAD src0_sel:WORD_1
	v_cvt_f32_f16_e32 v108, v241
	v_cvt_f32_f16_sdwa v114, v243 dst_sel:DWORD dst_unused:UNUSED_PAD src0_sel:WORD_1
	v_cvt_f32_f16_e32 v115, v243
	s_waitcnt vmcnt(3)
	v_sub_f32_e32 v106, v106, v204
	v_sub_f32_e32 v107, v107, v204
	v_sub_f32_e32 v108, v108, v204
	v_sub_f32_e32 v109, v109, v204
	v_pk_mul_f32 v[106:107], v[204:205], v[106:107] op_sel:[1,0]
	v_pk_mul_f32 v[108:109], v[204:205], v[108:109] op_sel:[1,0]
	v_pk_fma_f32 v[106:107], v[182:183], v[106:107], v[194:195]
	v_pk_fma_f32 v[108:109], v[180:181], v[108:109], v[192:193]
	v_pk_fma_f32 v[100:101], v[100:101], v[174:175], v[106:107]
	v_sub_f32_e32 v106, v111, v204
	v_sub_f32_e32 v107, v110, v204
	v_pk_fma_f32 v[102:103], v[102:103], v[172:173], v[108:109]
	v_sub_f32_e32 v108, v115, v204
	v_sub_f32_e32 v109, v114, v204
	v_pk_mul_f32 v[106:107], v[204:205], v[106:107] op_sel:[1,0]
	v_pk_mul_f32 v[108:109], v[204:205], v[108:109] op_sel:[1,0]
	v_pk_fma_f32 v[106:107], v[186:187], v[106:107], v[190:191]
	v_pk_fma_f32 v[108:109], v[184:185], v[108:109], v[188:189]
	v_pk_fma_f32 v[96:97], v[96:97], v[178:179], v[106:107]
	v_pk_fma_f32 v[108:109], v[98:99], v[176:177], v[108:109]
	v_cvt_pkrtz_f16_f32 v98, v100, v101
	v_cvt_pkrtz_f16_f32 v100, v96, v97
	v_lshl_add_u64 v[96:97], s[24:25], 0, v[202:203]
	v_cvt_pkrtz_f16_f32 v99, v102, v103
	v_cvt_pkrtz_f16_f32 v101, v108, v109
	v_lshl_add_u64 v[96:97], v[96:97], 0, v[196:197]
	global_store_dwordx4 v[96:97], v[98:101], off
	s_mov_b64 s[30:31], 0x40000
	v_lshl_add_u64 v[118:119], v[200:201], 0, s[30:31]
	s_mov_b64 s[30:31], 0x48000
	v_lshl_add_u64 v[126:127], v[200:201], 0, s[30:31]
	s_mov_b64 s[30:31], 0x50000
	v_lshl_add_u64 v[150:151], v[200:201], 0, s[30:31]
	s_mov_b64 s[30:31], 0x58000
	v_lshl_add_u64 v[98:99], v[198:199], 0, v[118:119]
	v_lshl_add_u64 v[102:103], v[198:199], 0, v[150:151]
	v_lshl_add_u64 v[202:203], v[200:201], 0, s[30:31]
	v_lshl_add_u64 v[100:101], v[198:199], 0, v[126:127]
	global_load_dwordx4 v[108:111], v[98:99], off nt
	global_load_dwordx4 v[114:117], v[100:101], off nt
	v_lshl_add_u64 v[106:107], v[198:199], 0, v[202:203]
	global_load_dwordx4 v[122:125], v[102:103], off nt
	global_load_dwordx4 v[198:201], v[106:107], off nt
	global_load_dwordx2 v[204:205], v[138:139], off offset:1024
	global_load_dwordx2 v[206:207], v[138:139], off offset:1152
	global_load_dwordx2 v[228:229], v[138:139], off offset:1280
	global_load_dwordx2 v[230:231], v[138:139], off offset:1408
	s_waitcnt vmcnt(7)
; DI unsigned pkh2(float lo, float hi) { return __builtin_bit_cast(unsigned, __builtin_amdgcn_cvt_pkrtz(lo, hi)); }
; DI float hlo(unsigned u) { return (float)__builtin_bit_cast(f16x2_t, u).x; }
; DI float hhi(unsigned u) { return (float)__builtin_bit_cast(f16x2_t, u).y; }
;     DI void operator()(const pg8::f32x4 (&acc)[2][2][4][2], const pg8::Unit& u, int wr, int wc, int fr, int fq) const {
;     ...
; #pragma unroll
;                 for (int m = 0; m < 4; ++m) {
;                     const f32x4 x0 = {hlo(xv[m].x), hhi(xv[m].x), hlo(xv[m].y), hhi(xv[m].y)}, x1 = {hlo(xv[m].z), hhi(xv[m].z), hlo(xv[m].w), hhi(xv[m].w)};
;                     const f32x4 y0 = (x0 - st[m].x) * st[m].y * gq[0] + bq[0] + gs[0] * acc[ai][bj][m][0];
;                     const f32x4 y1 = (x1 - st[m].x) * st[m].y * gq[1] + bq[1] + gs[1] * acc[ai][bj][m][1];
;                     u32x4 w; w.x = pkh2(y0.x, y0.y); w.y = pkh2(y0.z, y0.w); w.z = pkh2(y1.x, y1.y); w.w = pkh2(y1.z, y1.w);
;                     *(u32x4*)(X + (size_t)(row0 + ai * 128 + m * 16) * DM + col0 + bj * 128) = w;
;                 }
	v_cvt_f32_f16_sdwa v145, v108 dst_sel:DWORD dst_unused:UNUSED_PAD src0_sel:WORD_1
	v_cvt_f32_f16_e32 v108, v108
	v_cvt_f32_f16_sdwa v209, v109 dst_sel:DWORD dst_unused:UNUSED_PAD src0_sel:WORD_1
	v_cvt_f32_f16_e32 v218, v109
	v_cvt_f32_f16_sdwa v219, v110 dst_sel:DWORD dst_unused:UNUSED_PAD src0_sel:WORD_1
	v_cvt_f32_f16_e32 v220, v110
	v_cvt_f32_f16_sdwa v227, v111 dst_sel:DWORD dst_unused:UNUSED_PAD src0_sel:WORD_1
	v_cvt_f32_f16_e32 v232, v111
	s_waitcnt vmcnt(3)
	v_sub_f32_e32 v108, v108, v204
	v_sub_f32_e32 v109, v145, v204
	v_sub_f32_e32 v110, v218, v204
	v_sub_f32_e32 v111, v209, v204
	v_pk_mul_f32 v[108:109], v[204:205], v[108:109] op_sel:[1,0]
	v_pk_mul_f32 v[110:111], v[204:205], v[110:111] op_sel:[1,0]
	v_pk_fma_f32 v[108:109], v[182:183], v[108:109], v[194:195]
	v_pk_fma_f32 v[110:111], v[180:181], v[110:111], v[192:193]
	v_pk_fma_f32 v[92:93], v[92:93], v[174:175], v[108:109]
	v_sub_f32_e32 v108, v220, v204
	v_sub_f32_e32 v109, v219, v204
	v_pk_fma_f32 v[94:95], v[94:95], v[172:173], v[110:111]
	v_sub_f32_e32 v110, v232, v204
	v_sub_f32_e32 v111, v227, v204
	v_pk_mul_f32 v[108:109], v[204:205], v[108:109] op_sel:[1,0]
	v_pk_mul_f32 v[110:111], v[204:205], v[110:111] op_sel:[1,0]
	v_pk_fma_f32 v[108:109], v[186:187], v[108:109], v[190:191]
	v_pk_fma_f32 v[110:111], v[184:185], v[110:111], v[188:189]
	v_pk_fma_f32 v[88:89], v[88:89], v[178:179], v[108:109]
	v_pk_fma_f32 v[110:111], v[90:91], v[176:177], v[110:111]
	v_cvt_pkrtz_f16_f32 v90, v92, v93
	v_cvt_pkrtz_f16_f32 v92, v88, v89
	v_lshl_add_u64 v[88:89], s[24:25], 0, v[118:119]
	v_cvt_pkrtz_f16_f32 v91, v94, v95
	v_cvt_pkrtz_f16_f32 v93, v110, v111
	v_lshl_add_u64 v[88:89], v[88:89], 0, v[196:197]
	global_store_dwordx4 v[88:89], v[90:93], off
	v_cvt_f32_f16_sdwa v94, v116 dst_sel:DWORD dst_unused:UNUSED_PAD src0_sel:WORD_1
	v_cvt_f32_f16_e32 v95, v116
	v_cvt_f32_f16_sdwa v91, v114 dst_sel:DWORD dst_unused:UNUSED_PAD src0_sel:WORD_1
	v_cvt_f32_f16_e32 v90, v114
	v_cvt_f32_f16_sdwa v93, v115 dst_sel:DWORD dst_unused:UNUSED_PAD src0_sel:WORD_1
	v_cvt_f32_f16_e32 v92, v115
	v_cvt_f32_f16_sdwa v108, v117 dst_sel:DWORD dst_unused:UNUSED_PAD src0_sel:WORD_1
	v_cvt_f32_f16_e32 v109, v117
	s_waitcnt vmcnt(3)
	v_sub_f32_e32 v90, v90, v206
	v_sub_f32_e32 v91, v91, v206
	v_sub_f32_e32 v92, v92, v206
	v_sub_f32_e32 v93, v93, v206
	v_pk_mul_f32 v[90:91], v[206:207], v[90:91] op_sel:[1,0]
	v_pk_mul_f32 v[92:93], v[206:207], v[92:93] op_sel:[1,0]
	v_pk_fma_f32 v[90:91], v[182:183], v[90:91], v[194:195]
	v_pk_fma_f32 v[92:93], v[180:181], v[92:93], v[192:193]
	v_pk_fma_f32 v[84:85], v[84:85], v[174:175], v[90:91]
	v_sub_f32_e32 v90, v95, v206
	v_sub_f32_e32 v91, v94, v206
	v_pk_fma_f32 v[86:87], v[86:87], v[172:173], v[92:93]
	v_sub_f32_e32 v92, v109, v206
	v_sub_f32_e32 v93, v108, v206
	v_pk_mul_f32 v[90:91], v[206:207], v[90:91] op_sel:[1,0]
	v_pk_mul_f32 v[92:93], v[206:207], v[92:93] op_sel:[1,0]
	v_pk_fma_f32 v[90:91], v[186:187], v[90:91], v[190:191]
	v_pk_fma_f32 v[92:93], v[184:185], v[92:93], v[188:189]
	v_pk_fma_f32 v[80:81], v[80:81], v[178:179], v[90:91]
	v_pk_fma_f32 v[92:93], v[82:83], v[176:177], v[92:93]
	v_cvt_pkrtz_f16_f32 v82, v84, v85
	v_cvt_pkrtz_f16_f32 v84, v80, v81
	v_lshl_add_u64 v[80:81], s[24:25], 0, v[126:127]
	v_cvt_pkrtz_f16_f32 v83, v86, v87
	v_cvt_pkrtz_f16_f32 v85, v92, v93
	v_lshl_add_u64 v[80:81], v[80:81], 0, v[196:197]
	global_store_dwordx4 v[80:81], v[82:85], off
	v_cvt_f32_f16_sdwa v86, v124 dst_sel:DWORD dst_unused:UNUSED_PAD src0_sel:WORD_1
	v_cvt_f32_f16_e32 v87, v124
	v_cvt_f32_f16_sdwa v83, v122 dst_sel:DWORD dst_unused:UNUSED_PAD src0_sel:WORD_1
	v_cvt_f32_f16_e32 v82, v122
	v_cvt_f32_f16_sdwa v85, v123 dst_sel:DWORD dst_unused:UNUSED_PAD src0_sel:WORD_1
	v_cvt_f32_f16_e32 v84, v123
	v_cvt_f32_f16_sdwa v90, v125 dst_sel:DWORD dst_unused:UNUSED_PAD src0_sel:WORD_1
	v_cvt_f32_f16_e32 v91, v125
	s_waitcnt vmcnt(3)
	v_sub_f32_e32 v82, v82, v228
	v_sub_f32_e32 v83, v83, v228
	v_sub_f32_e32 v84, v84, v228
	v_sub_f32_e32 v85, v85, v228
	v_pk_mul_f32 v[82:83], v[228:229], v[82:83] op_sel:[1,0]
	v_pk_mul_f32 v[84:85], v[228:229], v[84:85] op_sel:[1,0]
	v_pk_fma_f32 v[82:83], v[182:183], v[82:83], v[194:195]
	v_pk_fma_f32 v[84:85], v[180:181], v[84:85], v[192:193]
	v_pk_fma_f32 v[76:77], v[76:77], v[174:175], v[82:83]
	v_sub_f32_e32 v82, v87, v228
	v_sub_f32_e32 v83, v86, v228
	v_pk_fma_f32 v[78:79], v[78:79], v[172:173], v[84:85]
	v_sub_f32_e32 v84, v91, v228
	v_sub_f32_e32 v85, v90, v228
	v_pk_mul_f32 v[82:83], v[228:229], v[82:83] op_sel:[1,0]
	v_pk_mul_f32 v[84:85], v[228:229], v[84:85] op_sel:[1,0]
	v_pk_fma_f32 v[82:83], v[186:187], v[82:83], v[190:191]
	v_pk_fma_f32 v[84:85], v[184:185], v[84:85], v[188:189]
	v_pk_fma_f32 v[72:73], v[72:73], v[178:179], v[82:83]
	v_pk_fma_f32 v[84:85], v[74:75], v[176:177], v[84:85]
	v_cvt_pkrtz_f16_f32 v74, v76, v77
	v_cvt_pkrtz_f16_f32 v76, v72, v73
	v_lshl_add_u64 v[72:73], s[24:25], 0, v[150:151]
	v_cvt_pkrtz_f16_f32 v75, v78, v79
	v_cvt_pkrtz_f16_f32 v77, v84, v85
	v_lshl_add_u64 v[72:73], v[72:73], 0, v[196:197]
	global_store_dwordx4 v[72:73], v[74:77], off
	v_cvt_f32_f16_sdwa v78, v200 dst_sel:DWORD dst_unused:UNUSED_PAD src0_sel:WORD_1
	v_cvt_f32_f16_e32 v79, v200
	v_cvt_f32_f16_sdwa v75, v198 dst_sel:DWORD dst_unused:UNUSED_PAD src0_sel:WORD_1
	v_cvt_f32_f16_e32 v74, v198
	v_cvt_f32_f16_sdwa v77, v199 dst_sel:DWORD dst_unused:UNUSED_PAD src0_sel:WORD_1
	v_cvt_f32_f16_e32 v76, v199
	v_cvt_f32_f16_sdwa v82, v201 dst_sel:DWORD dst_unused:UNUSED_PAD src0_sel:WORD_1
	v_cvt_f32_f16_e32 v83, v201
	s_waitcnt vmcnt(3)
; DI unsigned pkh2(float lo, float hi) { return __builtin_bit_cast(unsigned, __builtin_amdgcn_cvt_pkrtz(lo, hi)); }
; DI float hlo(unsigned u) { return (float)__builtin_bit_cast(f16x2_t, u).x; }
; DI float hhi(unsigned u) { return (float)__builtin_bit_cast(f16x2_t, u).y; }
;     DI void operator()(const pg8::f32x4 (&acc)[2][2][4][2], const pg8::Unit& u, int wr, int wc, int fr, int fq) const {
;     ...
;         for (int bj = 0; bj < 2; ++bj) {
;             f32x4 gs[2], gq[2], bq[2];
; #pragma unroll
;             for (int n = 0; n < 2; ++n) { const f32x4 g = *(const f32x4*)(gp + col0 + bj * 128 + 4 * n); gs[n] = (g + 1.0f) * scale;
;                 gq[n] = *(const f32x4*)(gprev + col0 + bj * 128 + 4 * n) * ALPHA; bq[n] = *(const f32x4*)(bprev + col0 + bj * 128 + 4 * n) * ALPHA; }
; #pragma unroll
;             for (int ai = 0; ai < 2; ++ai) {
;                 u32x4 xv[4]; f32x2 st[4];
; #pragma unroll
;                 for (int m = 0; m < 4; ++m) { const int row = row0 + ai * 128 + m * 16; xv[m] = *(const u32x4*)(X + (size_t)row * DM + col0 + bj * 128); st[m] = stat[row]; }
;                 __builtin_amdgcn_sched_barrier(0);
; #pragma unroll
;                 for (int m = 0; m < 4; ++m) {
;                     const f32x4 x0 = {hlo(xv[m].x), hhi(xv[m].x), hlo(xv[m].y), hhi(xv[m].y)}, x1 = {hlo(xv[m].z), hhi(xv[m].z), hlo(xv[m].w), hhi(xv[m].w)};
;                     const f32x4 y0 = (x0 - st[m].x) * st[m].y * gq[0] + bq[0] + gs[0] * acc[ai][bj][m][0];
;                     const f32x4 y1 = (x1 - st[m].x) * st[m].y * gq[1] + bq[1] + gs[1] * acc[ai][bj][m][1];
;                     u32x4 w; w.x = pkh2(y0.x, y0.y); w.y = pkh2(y0.z, y0.w); w.z = pkh2(y1.x, y1.y); w.w = pkh2(y1.z, y1.w);
;                     *(u32x4*)(X + (size_t)(row0 + ai * 128 + m * 16) * DM + col0 + bj * 128) = w;
;                 }
	v_sub_f32_e32 v74, v74, v230
	v_sub_f32_e32 v75, v75, v230
	v_sub_f32_e32 v76, v76, v230
	v_sub_f32_e32 v77, v77, v230
	v_pk_mul_f32 v[74:75], v[230:231], v[74:75] op_sel:[1,0]
	v_pk_mul_f32 v[76:77], v[230:231], v[76:77] op_sel:[1,0]
	v_pk_fma_f32 v[74:75], v[182:183], v[74:75], v[194:195]
	v_pk_fma_f32 v[76:77], v[180:181], v[76:77], v[192:193]
	v_pk_fma_f32 v[68:69], v[68:69], v[174:175], v[74:75]
	v_sub_f32_e32 v74, v79, v230
	v_sub_f32_e32 v75, v78, v230
	v_pk_fma_f32 v[70:71], v[70:71], v[172:173], v[76:77]
	v_sub_f32_e32 v76, v83, v230
	v_sub_f32_e32 v77, v82, v230
	v_pk_mul_f32 v[74:75], v[230:231], v[74:75] op_sel:[1,0]
	v_pk_mul_f32 v[76:77], v[230:231], v[76:77] op_sel:[1,0]
	v_pk_fma_f32 v[74:75], v[186:187], v[74:75], v[190:191]
	v_pk_fma_f32 v[76:77], v[184:185], v[76:77], v[188:189]
	v_pk_fma_f32 v[64:65], v[64:65], v[178:179], v[74:75]
	v_pk_fma_f32 v[76:77], v[66:67], v[176:177], v[76:77]
	v_cvt_pkrtz_f16_f32 v66, v68, v69
	v_cvt_pkrtz_f16_f32 v68, v64, v65
	v_lshl_add_u64 v[64:65], s[24:25], 0, v[202:203]
	v_cvt_pkrtz_f16_f32 v67, v70, v71
	v_cvt_pkrtz_f16_f32 v69, v76, v77
	v_lshl_add_u64 v[64:65], v[64:65], 0, v[196:197]
	global_store_dwordx4 v[64:65], v[66:69], off
	global_load_dwordx4 v[76:79], v[158:159], off offset:528
	global_load_dwordx4 v[66:69], v[158:159], off offset:512
	global_load_dwordx4 v[84:87], v[154:155], off offset:528
	global_load_dwordx4 v[90:93], v[154:155], off offset:512
	global_load_dwordx4 v[108:111], v[142:143], off offset:528
	global_load_dwordx4 v[172:175], v[142:143], off offset:512
	global_load_dwordx4 v[176:179], v[156:157], off offset:256 nt
	global_load_dwordx2 v[118:119], v[138:139], off
	global_load_dwordx4 v[114:117], v[160:161], off offset:256 nt
	global_load_dwordx2 v[126:127], v[162:163], off
	global_load_dwordx4 v[122:125], v[164:165], off offset:256 nt
	global_load_dwordx2 v[142:143], v[166:167], off
	global_load_dwordx4 v[154:157], v[168:169], off offset:256 nt
	global_load_dwordx2 v[150:151], v[170:171], off
	s_nop 0
	s_waitcnt vmcnt(13)
	v_pk_add_f32 v[78:79], v[78:79], 1.0 op_sel_hi:[1,0]
	s_waitcnt vmcnt(12)
	v_pk_add_f32 v[68:69], v[68:69], 1.0 op_sel_hi:[1,0]
	v_pk_add_f32 v[70:71], v[66:67], 1.0 op_sel_hi:[1,0]
	v_pk_mul_f32 v[66:67], v[140:141], v[68:69] op_sel_hi:[0,1]
	v_pk_mul_f32 v[68:69], v[140:141], v[70:71] op_sel_hi:[0,1]
	s_waitcnt vmcnt(10)
	v_pk_mul_f32 v[70:71], v[92:93], s[34:35] op_sel_hi:[1,0]
	v_pk_mul_f32 v[74:75], v[90:91], s[34:35] op_sel_hi:[1,0]
	v_pk_add_f32 v[82:83], v[76:77], 1.0 op_sel_hi:[1,0]
	v_pk_mul_f32 v[76:77], v[140:141], v[78:79] op_sel_hi:[0,1]
	v_pk_mul_f32 v[78:79], v[140:141], v[82:83] op_sel_hi:[0,1]
	v_pk_mul_f32 v[82:83], v[86:87], s[34:35] op_sel_hi:[1,0]
	v_pk_mul_f32 v[84:85], v[84:85], s[34:35] op_sel_hi:[1,0]
	s_waitcnt vmcnt(9)
	v_pk_mul_f32 v[86:87], v[110:111], s[34:35] op_sel_hi:[1,0]
	s_waitcnt vmcnt(8)
	v_pk_mul_f32 v[94:95], v[172:173], s[34:35] op_sel_hi:[1,0]
	v_pk_mul_f32 v[172:173], v[108:109], s[34:35] op_sel_hi:[1,0]
	v_pk_mul_f32 v[174:175], v[174:175], s[34:35] op_sel_hi:[1,0]
	v_mov_b32_e32 v90, v172
	v_mov_b32_e32 v91, v173
	v_mov_b32_e32 v92, v174
	v_mov_b32_e32 v93, v175
	s_waitcnt vmcnt(7)
	v_cvt_f32_f16_sdwa v140, v176 dst_sel:DWORD dst_unused:UNUSED_PAD src0_sel:WORD_1
	v_cvt_f32_f16_e32 v108, v176
	v_cvt_f32_f16_sdwa v145, v177 dst_sel:DWORD dst_unused:UNUSED_PAD src0_sel:WORD_1
	v_cvt_f32_f16_e32 v158, v177
	v_cvt_f32_f16_sdwa v159, v178 dst_sel:DWORD dst_unused:UNUSED_PAD src0_sel:WORD_1
	v_cvt_f32_f16_e32 v160, v178
	v_cvt_f32_f16_sdwa v161, v179 dst_sel:DWORD dst_unused:UNUSED_PAD src0_sel:WORD_1
	v_cvt_f32_f16_e32 v162, v179
	s_waitcnt vmcnt(6)
	v_sub_f32_e32 v108, v108, v118
	v_sub_f32_e32 v109, v140, v118
	v_sub_f32_e32 v110, v158, v118
	v_sub_f32_e32 v111, v145, v118
	v_pk_mul_f32 v[110:111], v[118:119], v[110:111] op_sel:[1,0]
	v_pk_mul_f32 v[108:109], v[118:119], v[108:109] op_sel:[1,0]
	v_pk_fma_f32 v[110:111], v[70:71], v[110:111], v[92:93]
	v_pk_fma_f32 v[108:109], v[74:75], v[108:109], v[94:95]
	v_pk_fma_f32 v[62:63], v[62:63], v[66:67], v[110:111]
	v_pk_fma_f32 v[60:61], v[60:61], v[68:69], v[108:109]
	v_sub_f32_e32 v108, v160, v118
	v_sub_f32_e32 v109, v159, v118
	v_sub_f32_e32 v110, v162, v118
	v_sub_f32_e32 v111, v161, v118
	v_pk_mul_f32 v[110:111], v[118:119], v[110:111] op_sel:[1,0]
	v_pk_mul_f32 v[108:109], v[118:119], v[108:109] op_sel:[1,0]
	v_pk_fma_f32 v[110:111], v[82:83], v[110:111], v[86:87]
	v_pk_fma_f32 v[108:109], v[84:85], v[108:109], v[90:91]
	v_pk_fma_f32 v[110:111], v[58:59], v[76:77], v[110:111]
	v_pk_fma_f32 v[58:59], v[56:57], v[78:79], v[108:109]
	v_cvt_pkrtz_f16_f32 v56, v60, v61
	v_cvt_pkrtz_f16_f32 v57, v62, v63
	v_cvt_pkrtz_f16_f32 v58, v58, v59
	v_cvt_pkrtz_f16_f32 v59, v110, v111
	global_store_dwordx4 v[120:121], v[56:59], off offset:256
	s_waitcnt vmcnt(6)
	v_cvt_f32_f16_sdwa v60, v116 dst_sel:DWORD dst_unused:UNUSED_PAD src0_sel:WORD_1
	v_cvt_f32_f16_e32 v61, v116
	v_cvt_f32_f16_sdwa v57, v114 dst_sel:DWORD dst_unused:UNUSED_PAD src0_sel:WORD_1
	v_cvt_f32_f16_e32 v56, v114
	v_cvt_f32_f16_sdwa v59, v115 dst_sel:DWORD dst_unused:UNUSED_PAD src0_sel:WORD_1
	v_cvt_f32_f16_e32 v58, v115
	v_cvt_f32_f16_sdwa v62, v117 dst_sel:DWORD dst_unused:UNUSED_PAD src0_sel:WORD_1
	v_cvt_f32_f16_e32 v63, v117
	s_waitcnt vmcnt(5)
; DI unsigned pkh2(float lo, float hi) { return __builtin_bit_cast(unsigned, __builtin_amdgcn_cvt_pkrtz(lo, hi)); }
; DI float hlo(unsigned u) { return (float)__builtin_bit_cast(f16x2_t, u).x; }
; DI float hhi(unsigned u) { return (float)__builtin_bit_cast(f16x2_t, u).y; }
;     DI void operator()(const pg8::f32x4 (&acc)[2][2][4][2], const pg8::Unit& u, int wr, int wc, int fr, int fq) const {
;     ...
;             for (int ai = 0; ai < 2; ++ai) {
;                 u32x4 xv[4]; f32x2 st[4];
; #pragma unroll
;                 for (int m = 0; m < 4; ++m) { const int row = row0 + ai * 128 + m * 16; xv[m] = *(const u32x4*)(X + (size_t)row * DM + col0 + bj * 128); st[m] = stat[row]; }
;                 __builtin_amdgcn_sched_barrier(0);
; #pragma unroll
;                 for (int m = 0; m < 4; ++m) {
;                     const f32x4 x0 = {hlo(xv[m].x), hhi(xv[m].x), hlo(xv[m].y), hhi(xv[m].y)}, x1 = {hlo(xv[m].z), hhi(xv[m].z), hlo(xv[m].w), hhi(xv[m].w)};
;                     const f32x4 y0 = (x0 - st[m].x) * st[m].y * gq[0] + bq[0] + gs[0] * acc[ai][bj][m][0];
;                     const f32x4 y1 = (x1 - st[m].x) * st[m].y * gq[1] + bq[1] + gs[1] * acc[ai][bj][m][1];
;                     u32x4 w; w.x = pkh2(y0.x, y0.y); w.y = pkh2(y0.z, y0.w); w.z = pkh2(y1.x, y1.y); w.w = pkh2(y1.z, y1.w);
;                     *(u32x4*)(X + (size_t)(row0 + ai * 128 + m * 16) * DM + col0 + bj * 128) = w;
;                 }
	v_sub_f32_e32 v56, v56, v126
	v_sub_f32_e32 v57, v57, v126
	v_sub_f32_e32 v58, v58, v126
	v_sub_f32_e32 v59, v59, v126
	v_pk_mul_f32 v[58:59], v[126:127], v[58:59] op_sel:[1,0]
	v_pk_mul_f32 v[56:57], v[126:127], v[56:57] op_sel:[1,0]
	v_pk_fma_f32 v[58:59], v[70:71], v[58:59], v[92:93]
	v_pk_fma_f32 v[56:57], v[74:75], v[56:57], v[94:95]
	v_pk_fma_f32 v[54:55], v[54:55], v[66:67], v[58:59]
	v_pk_fma_f32 v[52:53], v[52:53], v[68:69], v[56:57]
	v_sub_f32_e32 v56, v61, v126
	v_sub_f32_e32 v57, v60, v126
	v_sub_f32_e32 v58, v63, v126
	v_sub_f32_e32 v59, v62, v126
	v_pk_mul_f32 v[58:59], v[126:127], v[58:59] op_sel:[1,0]
	v_pk_mul_f32 v[56:57], v[126:127], v[56:57] op_sel:[1,0]
	v_pk_fma_f32 v[58:59], v[82:83], v[58:59], v[86:87]
	v_pk_fma_f32 v[56:57], v[84:85], v[56:57], v[90:91]
	v_pk_fma_f32 v[58:59], v[50:51], v[76:77], v[58:59]
	v_pk_fma_f32 v[50:51], v[48:49], v[78:79], v[56:57]
	v_cvt_pkrtz_f16_f32 v48, v52, v53
	v_cvt_pkrtz_f16_f32 v49, v54, v55
	v_cvt_pkrtz_f16_f32 v50, v50, v51
	v_cvt_pkrtz_f16_f32 v51, v58, v59
	global_store_dwordx4 v[112:113], v[48:51], off offset:256
	s_waitcnt vmcnt(5)
	v_cvt_f32_f16_sdwa v52, v124 dst_sel:DWORD dst_unused:UNUSED_PAD src0_sel:WORD_1
	v_cvt_f32_f16_e32 v53, v124
	v_cvt_f32_f16_sdwa v49, v122 dst_sel:DWORD dst_unused:UNUSED_PAD src0_sel:WORD_1
	v_cvt_f32_f16_e32 v48, v122
	v_cvt_f32_f16_sdwa v51, v123 dst_sel:DWORD dst_unused:UNUSED_PAD src0_sel:WORD_1
	v_cvt_f32_f16_e32 v50, v123
	v_cvt_f32_f16_sdwa v54, v125 dst_sel:DWORD dst_unused:UNUSED_PAD src0_sel:WORD_1
	v_cvt_f32_f16_e32 v55, v125
	s_waitcnt vmcnt(4)
	v_sub_f32_e32 v48, v48, v142
	v_sub_f32_e32 v49, v49, v142
	v_sub_f32_e32 v50, v50, v142
	v_sub_f32_e32 v51, v51, v142
	v_pk_mul_f32 v[50:51], v[142:143], v[50:51] op_sel:[1,0]
	v_pk_mul_f32 v[48:49], v[142:143], v[48:49] op_sel:[1,0]
	v_pk_fma_f32 v[50:51], v[70:71], v[50:51], v[92:93]
	v_pk_fma_f32 v[48:49], v[74:75], v[48:49], v[94:95]
	v_pk_fma_f32 v[46:47], v[46:47], v[66:67], v[50:51]
	v_pk_fma_f32 v[44:45], v[44:45], v[68:69], v[48:49]
	v_sub_f32_e32 v48, v53, v142
	v_sub_f32_e32 v49, v52, v142
	v_sub_f32_e32 v50, v55, v142
	v_sub_f32_e32 v51, v54, v142
	v_pk_mul_f32 v[50:51], v[142:143], v[50:51] op_sel:[1,0]
	v_pk_mul_f32 v[48:49], v[142:143], v[48:49] op_sel:[1,0]
	v_pk_fma_f32 v[50:51], v[82:83], v[50:51], v[86:87]
	v_pk_fma_f32 v[48:49], v[84:85], v[48:49], v[90:91]
	v_pk_fma_f32 v[50:51], v[42:43], v[76:77], v[50:51]
	v_pk_fma_f32 v[42:43], v[40:41], v[78:79], v[48:49]
	v_cvt_pkrtz_f16_f32 v40, v44, v45
	v_cvt_pkrtz_f16_f32 v41, v46, v47
	v_cvt_pkrtz_f16_f32 v42, v42, v43
	v_cvt_pkrtz_f16_f32 v43, v50, v51
	global_store_dwordx4 v[104:105], v[40:43], off offset:256
	s_waitcnt vmcnt(4)
	v_cvt_f32_f16_sdwa v44, v156 dst_sel:DWORD dst_unused:UNUSED_PAD src0_sel:WORD_1
	v_cvt_f32_f16_e32 v45, v156
	v_cvt_f32_f16_sdwa v41, v154 dst_sel:DWORD dst_unused:UNUSED_PAD src0_sel:WORD_1
	v_cvt_f32_f16_e32 v40, v154
	v_cvt_f32_f16_sdwa v43, v155 dst_sel:DWORD dst_unused:UNUSED_PAD src0_sel:WORD_1
	v_cvt_f32_f16_e32 v42, v155
	v_cvt_f32_f16_sdwa v46, v157 dst_sel:DWORD dst_unused:UNUSED_PAD src0_sel:WORD_1
	v_cvt_f32_f16_e32 v47, v157
	s_waitcnt vmcnt(3)
	v_sub_f32_e32 v40, v40, v150
	v_sub_f32_e32 v41, v41, v150
	v_sub_f32_e32 v42, v42, v150
	v_sub_f32_e32 v43, v43, v150
	v_pk_mul_f32 v[42:43], v[150:151], v[42:43] op_sel:[1,0]
	v_pk_mul_f32 v[40:41], v[150:151], v[40:41] op_sel:[1,0]
	v_pk_fma_f32 v[42:43], v[70:71], v[42:43], v[92:93]
	v_pk_fma_f32 v[40:41], v[74:75], v[40:41], v[94:95]
	v_pk_fma_f32 v[38:39], v[38:39], v[66:67], v[42:43]
	v_pk_fma_f32 v[36:37], v[36:37], v[68:69], v[40:41]
	v_sub_f32_e32 v40, v45, v150
	v_sub_f32_e32 v41, v44, v150
	v_sub_f32_e32 v42, v47, v150
	v_sub_f32_e32 v43, v46, v150
	v_pk_mul_f32 v[42:43], v[150:151], v[42:43] op_sel:[1,0]
	v_pk_mul_f32 v[40:41], v[150:151], v[40:41] op_sel:[1,0]
	v_pk_fma_f32 v[42:43], v[82:83], v[42:43], v[86:87]
	v_pk_fma_f32 v[40:41], v[84:85], v[40:41], v[90:91]
	v_pk_fma_f32 v[42:43], v[34:35], v[76:77], v[42:43]
	v_pk_fma_f32 v[34:35], v[32:33], v[78:79], v[40:41]
	v_cvt_pkrtz_f16_f32 v32, v36, v37
	v_cvt_pkrtz_f16_f32 v33, v38, v39
	v_cvt_pkrtz_f16_f32 v34, v34, v35
	v_cvt_pkrtz_f16_f32 v35, v42, v43
	global_store_dwordx4 v[96:97], v[32:35], off offset:256
	global_load_dwordx4 v[32:35], v[98:99], off offset:256 nt
	s_nop 0
	global_load_dwordx4 v[36:39], v[100:101], off offset:256 nt
	global_load_dwordx4 v[40:43], v[102:103], off offset:256 nt
	global_load_dwordx4 v[44:47], v[106:107], off offset:256 nt
	global_load_dwordx2 v[48:49], v[138:139], off offset:1024
	global_load_dwordx2 v[50:51], v[138:139], off offset:1152
	global_load_dwordx2 v[52:53], v[138:139], off offset:1280
	global_load_dwordx2 v[54:55], v[138:139], off offset:1408
	s_waitcnt vmcnt(7)
	v_cvt_f32_f16_sdwa v56, v32 dst_sel:DWORD dst_unused:UNUSED_PAD src0_sel:WORD_1
	v_cvt_f32_f16_e32 v32, v32
	v_cvt_f32_f16_sdwa v57, v33 dst_sel:DWORD dst_unused:UNUSED_PAD src0_sel:WORD_1
	v_cvt_f32_f16_e32 v58, v33
	v_cvt_f32_f16_sdwa v59, v34 dst_sel:DWORD dst_unused:UNUSED_PAD src0_sel:WORD_1
	v_cvt_f32_f16_e32 v60, v34
	v_cvt_f32_f16_sdwa v61, v35 dst_sel:DWORD dst_unused:UNUSED_PAD src0_sel:WORD_1
	v_cvt_f32_f16_e32 v62, v35
	s_waitcnt vmcnt(3)
; DI unsigned pkh2(float lo, float hi) { return __builtin_bit_cast(unsigned, __builtin_amdgcn_cvt_pkrtz(lo, hi)); }
; DI float hlo(unsigned u) { return (float)__builtin_bit_cast(f16x2_t, u).x; }
; DI float hhi(unsigned u) { return (float)__builtin_bit_cast(f16x2_t, u).y; }
;     DI void operator()(const pg8::f32x4 (&acc)[2][2][4][2], const pg8::Unit& u, int wr, int wc, int fr, int fq) const {
;     ...
; #pragma unroll
;                 for (int m = 0; m < 4; ++m) {
;                     const f32x4 x0 = {hlo(xv[m].x), hhi(xv[m].x), hlo(xv[m].y), hhi(xv[m].y)}, x1 = {hlo(xv[m].z), hhi(xv[m].z), hlo(xv[m].w), hhi(xv[m].w)};
;                     const f32x4 y0 = (x0 - st[m].x) * st[m].y * gq[0] + bq[0] + gs[0] * acc[ai][bj][m][0];
;                     const f32x4 y1 = (x1 - st[m].x) * st[m].y * gq[1] + bq[1] + gs[1] * acc[ai][bj][m][1];
;                     u32x4 w; w.x = pkh2(y0.x, y0.y); w.y = pkh2(y0.z, y0.w); w.z = pkh2(y1.x, y1.y); w.w = pkh2(y1.z, y1.w);
;                     *(u32x4*)(X + (size_t)(row0 + ai * 128 + m * 16) * DM + col0 + bj * 128) = w;
;                 }
;                 __builtin_amdgcn_sched_barrier(0);
	v_sub_f32_e32 v32, v32, v48
	v_sub_f32_e32 v33, v56, v48
	v_sub_f32_e32 v34, v58, v48
	v_sub_f32_e32 v35, v57, v48
	v_pk_mul_f32 v[34:35], v[48:49], v[34:35] op_sel:[1,0]
	v_pk_mul_f32 v[32:33], v[48:49], v[32:33] op_sel:[1,0]
	v_pk_fma_f32 v[34:35], v[70:71], v[34:35], v[92:93]
	v_pk_fma_f32 v[32:33], v[74:75], v[32:33], v[94:95]
	v_pk_fma_f32 v[30:31], v[30:31], v[66:67], v[34:35]
	v_pk_fma_f32 v[28:29], v[28:29], v[68:69], v[32:33]
	v_sub_f32_e32 v32, v60, v48
	v_sub_f32_e32 v33, v59, v48
	v_sub_f32_e32 v34, v62, v48
	v_sub_f32_e32 v35, v61, v48
	v_pk_mul_f32 v[34:35], v[48:49], v[34:35] op_sel:[1,0]
	v_pk_mul_f32 v[32:33], v[48:49], v[32:33] op_sel:[1,0]
	v_pk_fma_f32 v[34:35], v[82:83], v[34:35], v[86:87]
	v_pk_fma_f32 v[32:33], v[84:85], v[32:33], v[90:91]
	v_pk_fma_f32 v[34:35], v[26:27], v[76:77], v[34:35]
	v_pk_fma_f32 v[26:27], v[24:25], v[78:79], v[32:33]
	v_cvt_pkrtz_f16_f32 v24, v28, v29
	v_cvt_pkrtz_f16_f32 v25, v30, v31
	v_cvt_pkrtz_f16_f32 v26, v26, v27
	v_cvt_pkrtz_f16_f32 v27, v34, v35
	global_store_dwordx4 v[88:89], v[24:27], off offset:256
	v_cvt_f32_f16_sdwa v28, v38 dst_sel:DWORD dst_unused:UNUSED_PAD src0_sel:WORD_1
	v_cvt_f32_f16_e32 v29, v38
	v_cvt_f32_f16_sdwa v25, v36 dst_sel:DWORD dst_unused:UNUSED_PAD src0_sel:WORD_1
	v_cvt_f32_f16_e32 v24, v36
	v_cvt_f32_f16_sdwa v27, v37 dst_sel:DWORD dst_unused:UNUSED_PAD src0_sel:WORD_1
	v_cvt_f32_f16_e32 v26, v37
	v_cvt_f32_f16_sdwa v30, v39 dst_sel:DWORD dst_unused:UNUSED_PAD src0_sel:WORD_1
	v_cvt_f32_f16_e32 v31, v39
	s_waitcnt vmcnt(3)
	v_sub_f32_e32 v24, v24, v50
	v_sub_f32_e32 v25, v25, v50
	v_sub_f32_e32 v26, v26, v50
	v_sub_f32_e32 v27, v27, v50
	v_pk_mul_f32 v[26:27], v[50:51], v[26:27] op_sel:[1,0]
	v_pk_mul_f32 v[24:25], v[50:51], v[24:25] op_sel:[1,0]
	v_pk_fma_f32 v[26:27], v[70:71], v[26:27], v[92:93]
	v_pk_fma_f32 v[24:25], v[74:75], v[24:25], v[94:95]
	v_pk_fma_f32 v[22:23], v[22:23], v[66:67], v[26:27]
	v_pk_fma_f32 v[20:21], v[20:21], v[68:69], v[24:25]
	v_sub_f32_e32 v24, v29, v50
	v_sub_f32_e32 v25, v28, v50
	v_sub_f32_e32 v26, v31, v50
	v_sub_f32_e32 v27, v30, v50
	v_pk_mul_f32 v[26:27], v[50:51], v[26:27] op_sel:[1,0]
	v_pk_mul_f32 v[24:25], v[50:51], v[24:25] op_sel:[1,0]
	v_pk_fma_f32 v[26:27], v[82:83], v[26:27], v[86:87]
	v_pk_fma_f32 v[24:25], v[84:85], v[24:25], v[90:91]
	v_pk_fma_f32 v[26:27], v[18:19], v[76:77], v[26:27]
	v_pk_fma_f32 v[18:19], v[16:17], v[78:79], v[24:25]
	v_cvt_pkrtz_f16_f32 v16, v20, v21
	v_cvt_pkrtz_f16_f32 v17, v22, v23
	v_cvt_pkrtz_f16_f32 v18, v18, v19
	v_cvt_pkrtz_f16_f32 v19, v26, v27
	global_store_dwordx4 v[80:81], v[16:19], off offset:256
	v_cvt_f32_f16_sdwa v20, v42 dst_sel:DWORD dst_unused:UNUSED_PAD src0_sel:WORD_1
	v_cvt_f32_f16_e32 v21, v42
	v_cvt_f32_f16_sdwa v17, v40 dst_sel:DWORD dst_unused:UNUSED_PAD src0_sel:WORD_1
	v_cvt_f32_f16_e32 v16, v40
	v_cvt_f32_f16_sdwa v19, v41 dst_sel:DWORD dst_unused:UNUSED_PAD src0_sel:WORD_1
	v_cvt_f32_f16_e32 v18, v41
	v_cvt_f32_f16_sdwa v22, v43 dst_sel:DWORD dst_unused:UNUSED_PAD src0_sel:WORD_1
	v_cvt_f32_f16_e32 v23, v43
	s_waitcnt vmcnt(3)
	v_sub_f32_e32 v16, v16, v52
	v_sub_f32_e32 v17, v17, v52
	v_sub_f32_e32 v18, v18, v52
	v_sub_f32_e32 v19, v19, v52
	v_pk_mul_f32 v[18:19], v[52:53], v[18:19] op_sel:[1,0]
	v_pk_mul_f32 v[16:17], v[52:53], v[16:17] op_sel:[1,0]
	v_pk_fma_f32 v[18:19], v[70:71], v[18:19], v[92:93]
	v_pk_fma_f32 v[16:17], v[74:75], v[16:17], v[94:95]
	v_pk_fma_f32 v[14:15], v[14:15], v[66:67], v[18:19]
	v_pk_fma_f32 v[12:13], v[12:13], v[68:69], v[16:17]
	v_sub_f32_e32 v16, v21, v52
	v_sub_f32_e32 v17, v20, v52
	v_sub_f32_e32 v18, v23, v52
	v_sub_f32_e32 v19, v22, v52
	v_pk_mul_f32 v[18:19], v[52:53], v[18:19] op_sel:[1,0]
	v_pk_mul_f32 v[16:17], v[52:53], v[16:17] op_sel:[1,0]
	v_pk_fma_f32 v[18:19], v[82:83], v[18:19], v[86:87]
	v_pk_fma_f32 v[16:17], v[84:85], v[16:17], v[90:91]
	v_pk_fma_f32 v[18:19], v[10:11], v[76:77], v[18:19]
	v_pk_fma_f32 v[10:11], v[8:9], v[78:79], v[16:17]
	v_cvt_pkrtz_f16_f32 v8, v12, v13
	v_cvt_pkrtz_f16_f32 v9, v14, v15
	v_cvt_pkrtz_f16_f32 v10, v10, v11
	v_cvt_pkrtz_f16_f32 v11, v18, v19
	global_store_dwordx4 v[72:73], v[8:11], off offset:256
	v_cvt_f32_f16_sdwa v12, v46 dst_sel:DWORD dst_unused:UNUSED_PAD src0_sel:WORD_1
	v_cvt_f32_f16_e32 v13, v46
	v_cvt_f32_f16_sdwa v9, v44 dst_sel:DWORD dst_unused:UNUSED_PAD src0_sel:WORD_1
	v_cvt_f32_f16_e32 v8, v44
	v_cvt_f32_f16_sdwa v11, v45 dst_sel:DWORD dst_unused:UNUSED_PAD src0_sel:WORD_1
	v_cvt_f32_f16_e32 v10, v45
	v_cvt_f32_f16_sdwa v14, v47 dst_sel:DWORD dst_unused:UNUSED_PAD src0_sel:WORD_1
	v_cvt_f32_f16_e32 v15, v47
	s_waitcnt vmcnt(3)
	v_sub_f32_e32 v8, v8, v54
	v_sub_f32_e32 v9, v9, v54
	v_sub_f32_e32 v10, v10, v54
	v_sub_f32_e32 v11, v11, v54
	v_pk_mul_f32 v[10:11], v[54:55], v[10:11] op_sel:[1,0]
	v_pk_mul_f32 v[8:9], v[54:55], v[8:9] op_sel:[1,0]
	v_pk_fma_f32 v[10:11], v[70:71], v[10:11], v[92:93]
	v_pk_fma_f32 v[8:9], v[74:75], v[8:9], v[94:95]
	v_pk_fma_f32 v[6:7], v[6:7], v[66:67], v[10:11]
	v_pk_fma_f32 v[4:5], v[4:5], v[68:69], v[8:9]
	v_sub_f32_e32 v8, v13, v54
	v_sub_f32_e32 v9, v12, v54
	v_sub_f32_e32 v10, v15, v54
	v_sub_f32_e32 v11, v14, v54
	v_pk_mul_f32 v[10:11], v[54:55], v[10:11] op_sel:[1,0]
	v_pk_mul_f32 v[8:9], v[54:55], v[8:9] op_sel:[1,0]
	v_pk_fma_f32 v[10:11], v[82:83], v[10:11], v[86:87]
	v_pk_fma_f32 v[8:9], v[84:85], v[8:9], v[90:91]
	v_pk_fma_f32 v[10:11], v[2:3], v[76:77], v[10:11]
	v_pk_fma_f32 v[2:3], v[0:1], v[78:79], v[8:9]
	v_cvt_pkrtz_f16_f32 v0, v4, v5
	v_cvt_pkrtz_f16_f32 v1, v6, v7
	v_cvt_pkrtz_f16_f32 v2, v2, v3
	v_cvt_pkrtz_f16_f32 v3, v10, v11
	global_store_dwordx4 v[64:65], v[0:3], off offset:256
	s_and_b64 vcc, exec, s[0:1]
	s_mov_b64 s[0:1], -1
	s_cbranch_vccnz .LBB0_869
	s_andn2_b64 vcc, exec, s[18:19]
	s_cbranch_vccnz .LBB0_868
	s_barrier
	s_branch .LBB0_868
